# dense attention loop hand-scheduled: cross-tile software pipeline, every MFMA carries 2 exp+2 add+1 cvt
# speedup vs baseline: 1.0264x; 1.0264x over previous
.LBB0_301:
	s_add_i32 s30, s27, s19
	s_cmpk_gt_i32 s30, 0x1ff
	s_mov_b64 s[12:13], -1
	s_cbranch_scc1 .LBB0_300
	s_ashr_i32 s28, s30, 8
	s_and_b32 s31, s26, 0x80
	s_mul_i32 s13, s28, 0x6000000
	s_mul_hi_i32 s12, s28, 0x6000000
	s_add_u32 s33, s37, s13
	s_addc_u32 s35, s40, s12
	s_lshl_b32 s12, s30, 1
	s_and_b32 s29, s12, 0x1c0
	s_lshl_b32 s12, s29, 1
	s_add_u32 s12, s33, s12
	s_addc_u32 s13, s35, 0
	s_and_b32 s34, s30, 0x80
	s_add_u32 s34, s33, s34
	s_addc_u32 s35, s35, 0
	s_lshl_b32 s30, s30, 9
	v_mov_b32_e32 v14, v0
	s_and_b32 s30, s30, 0x3e00
	v_mov_b32_e32 v11, v171
	v_readfirstlane_b32 s33, v14
	s_andn2_b32 s33, s33, 63
	v_and_or_b32 v2, v14, 31, s30
	v_bfe_u32 v15, v14, 5, 1
	v_add_u32_e32 v172, s33, v2
	v_mov_b64_e32 v[2:3], s[12:13]
	v_mad_i64_i32 v[2:3], s[12:13], v172, s20, v[2:3]
	v_lshlrev_b32_e32 v170, 4, v15
	v_lshl_add_u64 v[2:3], v[2:3], 0, v[170:171]
	v_lshl_add_u64 v[4:5], v[2:3], 0, s[6:7]
	v_add_co_u32_e32 v6, vcc, s21, v2
	v_ashrrev_i32_e32 v16, 3, v14
	s_nop 0
	v_addc_co_u32_e32 v7, vcc, 0, v3, vcc
	global_load_dwordx4 v[130:133], v[2:3], off
	global_load_dwordx4 v[134:137], v[2:3], off offset:32
	global_load_dwordx4 v[138:141], v[4:5], off offset:32
	global_load_dwordx4 v[142:145], v[4:5], off offset:64
	global_load_dwordx4 v[146:149], v[2:3], off offset:64
	global_load_dwordx4 v[150:153], v[2:3], off offset:96
	global_load_dwordx4 v[154:157], v[6:7], off
	global_load_dwordx4 v[158:161], v[4:5], off offset:96
	v_mov_b64_e32 v[2:3], s[34:35]
	v_lshlrev_b32_e32 v4, 4, v14
	v_mad_i64_i32 v[2:3], s[12:13], v16, s20, v[2:3]
	v_and_b32_e32 v10, 0x70, v4
	v_lshl_add_u64 v[12:13], v[2:3], 0, v[10:11]
	global_load_dwordx4 v[2:5], v[12:13], off offset:1024
	global_load_dwordx4 v[6:9], v[12:13], off offset:1280
	v_add_co_u32_e32 v12, vcc, s23, v12
	s_waitcnt lgkmcnt(0)
	s_nop 0
	v_addc_co_u32_e32 v13, vcc, 0, v13, vcc
	s_barrier
	global_load_dwordx4 v[162:165], v[12:13], off offset:1024
	global_load_dwordx4 v[166:169], v[12:13], off offset:1280
	v_lshlrev_b32_e32 v12, 1, v14
	v_lshrrev_b32_e32 v13, 1, v14
	v_lshlrev_b32_e32 v174, 3, v15
	v_and_b32_e32 v15, 8, v12
	v_and_b32_e32 v18, 4, v13
	v_and_b32_e32 v173, 32, v12
	v_mad_i64_i32 v[12:13], s[12:13], v16, s20, 0
	v_and_b32_e32 v11, 19, v14
	v_lshrrev_b32_e32 v17, 2, v14
	v_lshlrev_b32_e32 v14, 3, v14
	v_mul_lo_u32 v19, v16, s22
	v_mad_i64_i32 v[12:13], s[12:13], s28, v1, v[12:13]
	v_mov_b32_e32 v50, 0
	v_and_b32_e32 v175, 24, v14
	v_or3_b32 v11, v11, v15, v18
	v_and_or_b32 v14, v17, 3, v174
	v_add3_u32 v180, 0, v19, v10
	v_or3_b32 v12, v12, s31, v10
	s_mov_b32 s33, 0
	s_mov_b32 s30, 0
	v_mov_b32_e32 v51, v50
	v_mov_b32_e32 v52, v50
	v_mov_b32_e32 v53, v50
	v_mov_b32_e32 v54, v50
	v_mov_b32_e32 v55, v50
	v_mov_b32_e32 v56, v50
	v_mov_b32_e32 v57, v50
	v_mov_b32_e32 v58, v50
	v_mul_u32_u24_e32 v181, 0x90, v11
	v_mul_u32_u24_e32 v182, 0x90, v14
	v_lshl_add_u64 v[176:177], s[4:5], 0, v[12:13]
	v_mov_b32_e32 v59, v50
	v_mov_b32_e32 v60, v50
	v_mov_b32_e32 v61, v50
	v_mov_b32_e32 v62, v50
	v_mov_b32_e32 v63, v50
	v_mov_b32_e32 v64, v50
	v_mov_b32_e32 v65, v50
	v_mov_b32_e32 v34, v50
	v_mov_b32_e32 v35, v50
	v_mov_b32_e32 v36, v50
	v_mov_b32_e32 v37, v50
	v_mov_b32_e32 v38, v50
	v_mov_b32_e32 v39, v50
	v_mov_b32_e32 v40, v50
	v_mov_b32_e32 v41, v50
	v_mov_b32_e32 v42, v50
	v_mov_b32_e32 v43, v50
	s_waitcnt vmcnt(3)
	ds_write_b128 v180, v[2:5]
	s_waitcnt vmcnt(2)
	ds_write_b128 v180, v[6:9] offset:9216
	s_waitcnt vmcnt(1)
	ds_write_b128 v180, v[162:165] offset:18432
	s_waitcnt vmcnt(0)
	ds_write_b128 v180, v[166:169] offset:27648
	v_mov_b32_e32 v44, v50
	v_mov_b32_e32 v45, v50
	v_mov_b32_e32 v46, v50
	v_mov_b32_e32 v47, v50
	v_mov_b32_e32 v48, v50
	v_mov_b32_e32 v49, v50
	v_mov_b32_e32 v2, v50
	v_mov_b32_e32 v3, v50
	v_mov_b32_e32 v4, v50
	v_mov_b32_e32 v5, v50
	v_mov_b32_e32 v6, v50
	v_mov_b32_e32 v7, v50
	v_mov_b32_e32 v8, v50
	v_mov_b32_e32 v9, v50
	v_mov_b32_e32 v10, v50
	v_mov_b32_e32 v11, v50
	v_mov_b32_e32 v12, v50
	v_mov_b32_e32 v13, v50
	v_mov_b32_e32 v14, v50
	v_mov_b32_e32 v15, v50
	v_mov_b32_e32 v16, v50
	v_mov_b32_e32 v17, v50
	v_mov_b32_e32 v18, v50
	v_mov_b32_e32 v19, v50
	v_mov_b32_e32 v20, v50
	v_mov_b32_e32 v21, v50
	v_mov_b32_e32 v22, v50
	v_mov_b32_e32 v23, v50
	v_mov_b32_e32 v24, v50
	v_mov_b32_e32 v25, v50
	v_mov_b32_e32 v26, v50
	v_mov_b32_e32 v27, v50
	v_mov_b32_e32 v28, v50
	v_mov_b32_e32 v29, v50
	v_mov_b32_e32 v30, v50
	v_mov_b32_e32 v31, v50
	v_mov_b32_e32 v32, v50
	v_mov_b32_e32 v33, v50
	v_mov_b32_e32 v178, v50
	v_mov_b32_e32 v179, v50
	v_mov_b32_e32 v218, 0
	v_mov_b32_e32 v219, 0
	v_mov_b32_e32 v220, 0
	v_mov_b32_e32 v221, 0
	v_mov_b32_e32 v222, 0
	v_mov_b32_e32 v223, 0
	v_mov_b32_e32 v226, 0
	v_mov_b32_e32 v227, 0
	v_mov_b32_e32 v208, 0
	v_mov_b32_e32 v209, 0
	v_mov_b32_e32 v210, 0
	v_mov_b32_e32 v211, 0
	v_mov_b32_e32 v212, 0
	v_mov_b32_e32 v213, 0
	v_mov_b32_e32 v214, 0
	v_mov_b32_e32 v215, 0
	v_mov_b32_e32 v106, 0
	v_mov_b32_e32 v107, 0
	v_mov_b32_e32 v108, 0
	v_mov_b32_e32 v109, 0
	v_mov_b32_e32 v122, 0
	v_mov_b32_e32 v123, 0
	v_mov_b32_e32 v124, 0
	v_mov_b32_e32 v125, 0
	s_waitcnt lgkmcnt(0)
	s_barrier
	v_add3_u32 v225, s33, v181, v170
	ds_read_b128 v[184:187], v225
	ds_read_b128 v[188:191], v225 offset:32
	ds_read_b128 v[192:195], v225 offset:64
	ds_read_b128 v[196:199], v225 offset:96
	s_waitcnt lgkmcnt(3)
	v_mfma_f32_32x32x16_bf16 v[66:81], v[184:187], v[130:133], 0
	s_waitcnt lgkmcnt(2)
	v_mfma_f32_32x32x16_bf16 v[66:81], v[188:191], v[134:137], v[66:81]
	s_waitcnt lgkmcnt(1)
	v_mfma_f32_32x32x16_bf16 v[66:81], v[192:195], v[146:149], v[66:81]
	s_waitcnt lgkmcnt(0)
	v_mfma_f32_32x32x16_bf16 v[66:81], v[196:199], v[150:153], v[66:81]
	v_mfma_f32_32x32x16_bf16 v[82:97], v[184:187], v[154:157], 0
	v_mfma_f32_32x32x16_bf16 v[82:97], v[188:191], v[138:141], v[82:97]
	v_mfma_f32_32x32x16_bf16 v[82:97], v[192:195], v[142:145], v[82:97]
	v_mfma_f32_32x32x16_bf16 v[82:97], v[196:199], v[158:161], v[82:97]
	s_branch .Lat_enter
.Lat_loop:
	s_waitcnt lgkmcnt(0)
	s_barrier
.Lat_enter:
	global_load_dwordx4 v[162:165], v[176:177], off
	global_load_dwordx4 v[166:169], v[176:177], off offset:256
	ds_read_b128 v[184:187], v225 offset:4608
	ds_read_b128 v[188:191], v225 offset:4640
	ds_read_b128 v[192:195], v225 offset:4672
	ds_read_b128 v[196:199], v225 offset:4704
	s_add_i32 s31, s33, 0x4800
	s_cmp_eq_u32 s31, 0xd800
	s_cselect_b32 s31, 0, s31
	s_add_i32 s12, s31, 0x4800
	s_cmp_eq_u32 s12, 0xd800
	s_cselect_b32 s12, 0, s12
	v_add_u32_e32 v224, s33, v182
	v_add3_u32 v216, v224, v173, v175
	v_add3_u32 v225, s31, v181, v170
	v_exp_f32_e32 v66, v66
	v_exp_f32_e32 v67, v67
	v_add_f32_e32 v178, v178, v66
	v_add_f32_e32 v218, v218, v67
	v_cvt_pk_bf16_f32 v66, v66, v67
	v_mfma_f32_32x32x16_bf16 v[50:65], v[208:211], v[106:109], v[50:65]
	v_exp_f32_e32 v68, v68
	v_exp_f32_e32 v69, v69
	v_add_f32_e32 v219, v219, v68
	v_add_f32_e32 v220, v220, v69
	v_cvt_pk_bf16_f32 v67, v68, v69
	v_mfma_f32_32x32x16_bf16 v[34:49], v[212:215], v[106:109], v[34:49]
	v_lshl_add_u64 v[176:177], v[176:177], 0, s[8:9]
	v_exp_f32_e32 v70, v70
	v_exp_f32_e32 v71, v71
	v_add_f32_e32 v178, v178, v70
	v_add_f32_e32 v218, v218, v71
	v_cvt_pk_bf16_f32 v68, v70, v71
	v_mfma_f32_32x32x16_bf16 v[18:33], v[208:211], v[122:125], v[18:33]
	v_exp_f32_e32 v72, v72
	v_exp_f32_e32 v73, v73
	v_add_f32_e32 v219, v219, v72
	v_add_f32_e32 v220, v220, v73
	v_cvt_pk_bf16_f32 v69, v72, v73
	v_mfma_f32_32x32x16_bf16 v[2:17], v[212:215], v[122:125], v[2:17]
	v_exp_f32_e32 v82, v82
	v_exp_f32_e32 v83, v83
	v_add_f32_e32 v179, v179, v82
	v_add_f32_e32 v221, v221, v83
	v_cvt_pk_bf16_f32 v82, v82, v83
	s_waitcnt lgkmcnt(3)
	v_mfma_f32_32x32x16_bf16 v[98:113], v[184:187], v[130:133], 0
	ds_read_b64_tr_b16 v[200:201], v216 offset:9216
	ds_read_b64_tr_b16 v[202:203], v216 offset:9792
	ds_read_b64_tr_b16 v[204:205], v216 offset:9280
	ds_read_b64_tr_b16 v[206:207], v216 offset:9856
	v_exp_f32_e32 v84, v84
	v_exp_f32_e32 v85, v85
	v_add_f32_e32 v222, v222, v84
	v_add_f32_e32 v223, v223, v85
	v_cvt_pk_bf16_f32 v83, v84, v85
	s_waitcnt lgkmcnt(6)
	v_mfma_f32_32x32x16_bf16 v[98:113], v[188:191], v[134:137], v[98:113]
	ds_read_b64_tr_b16 v[208:209], v216 offset:11520
	ds_read_b64_tr_b16 v[210:211], v216 offset:12096
	ds_read_b64_tr_b16 v[212:213], v216 offset:11584
	ds_read_b64_tr_b16 v[214:215], v216 offset:12160
	v_exp_f32_e32 v86, v86
	v_exp_f32_e32 v87, v87
	v_add_f32_e32 v179, v179, v86
	v_add_f32_e32 v221, v221, v87
	v_cvt_pk_bf16_f32 v84, v86, v87
	s_waitcnt lgkmcnt(9)
	v_mfma_f32_32x32x16_bf16 v[98:113], v[192:195], v[146:149], v[98:113]
	v_exp_f32_e32 v88, v88
	v_exp_f32_e32 v89, v89
	v_add_f32_e32 v222, v222, v88
	v_add_f32_e32 v223, v223, v89
	v_cvt_pk_bf16_f32 v85, v88, v89
	s_waitcnt lgkmcnt(8)
	v_mfma_f32_32x32x16_bf16 v[98:113], v[196:199], v[150:153], v[98:113]
	v_exp_f32_e32 v74, v74
	v_exp_f32_e32 v75, v75
	v_add_f32_e32 v178, v178, v74
	v_add_f32_e32 v218, v218, v75
	v_cvt_pk_bf16_f32 v74, v74, v75
	v_mfma_f32_32x32x16_bf16 v[114:129], v[184:187], v[154:157], 0
	v_exp_f32_e32 v76, v76
	v_exp_f32_e32 v77, v77
	v_add_f32_e32 v219, v219, v76
	v_add_f32_e32 v220, v220, v77
	v_cvt_pk_bf16_f32 v75, v76, v77
	v_mfma_f32_32x32x16_bf16 v[114:129], v[188:191], v[138:141], v[114:129]
	v_exp_f32_e32 v78, v78
	v_exp_f32_e32 v79, v79
	v_add_f32_e32 v178, v178, v78
	v_add_f32_e32 v218, v218, v79
	v_cvt_pk_bf16_f32 v76, v78, v79
	v_mfma_f32_32x32x16_bf16 v[114:129], v[192:195], v[142:145], v[114:129]
	v_exp_f32_e32 v80, v80
	v_exp_f32_e32 v81, v81
	v_add_f32_e32 v219, v219, v80
	v_add_f32_e32 v220, v220, v81
	v_cvt_pk_bf16_f32 v77, v80, v81
	v_mfma_f32_32x32x16_bf16 v[114:129], v[196:199], v[158:161], v[114:129]
	v_exp_f32_e32 v90, v90
	v_exp_f32_e32 v91, v91
	v_add_f32_e32 v179, v179, v90
	v_add_f32_e32 v221, v221, v91
	v_cvt_pk_bf16_f32 v90, v90, v91
	s_waitcnt lgkmcnt(6)
	v_mfma_f32_32x32x16_bf16 v[50:65], v[200:203], v[66:69], v[50:65]
	ds_read_b128 v[184:187], v225
	ds_read_b128 v[188:191], v225 offset:32
	ds_read_b128 v[192:195], v225 offset:64
	ds_read_b128 v[196:199], v225 offset:96
	v_exp_f32_e32 v92, v92
	v_exp_f32_e32 v93, v93
	v_add_f32_e32 v222, v222, v92
	v_add_f32_e32 v223, v223, v93
	v_cvt_pk_bf16_f32 v91, v92, v93
	s_waitcnt lgkmcnt(8)
	v_mfma_f32_32x32x16_bf16 v[34:49], v[204:207], v[66:69], v[34:49]
	v_exp_f32_e32 v94, v94
	v_exp_f32_e32 v95, v95
	v_add_f32_e32 v179, v179, v94
	v_add_f32_e32 v221, v221, v95
	v_cvt_pk_bf16_f32 v92, v94, v95
	v_mfma_f32_32x32x16_bf16 v[18:33], v[200:203], v[82:85], v[18:33]
	v_exp_f32_e32 v96, v96
	v_exp_f32_e32 v97, v97
	v_add_f32_e32 v222, v222, v96
	v_add_f32_e32 v223, v223, v97
	v_cvt_pk_bf16_f32 v93, v96, v97
	v_mfma_f32_32x32x16_bf16 v[2:17], v[204:207], v[82:85], v[2:17]
	v_exp_f32_e32 v98, v98
	v_exp_f32_e32 v99, v99
	v_add_f32_e32 v178, v178, v98
	v_add_f32_e32 v218, v218, v99
	v_cvt_pk_bf16_f32 v98, v98, v99
	s_waitcnt lgkmcnt(6)
	v_mfma_f32_32x32x16_bf16 v[50:65], v[208:211], v[74:77], v[50:65]
	ds_read_b64_tr_b16 v[200:201], v216 offset:13824
	ds_read_b64_tr_b16 v[202:203], v216 offset:14400
	ds_read_b64_tr_b16 v[204:205], v216 offset:13888
	ds_read_b64_tr_b16 v[206:207], v216 offset:14464
	v_exp_f32_e32 v100, v100
	v_exp_f32_e32 v101, v101
	v_add_f32_e32 v219, v219, v100
	v_add_f32_e32 v220, v220, v101
	v_cvt_pk_bf16_f32 v99, v100, v101
	s_waitcnt lgkmcnt(8)
	v_mfma_f32_32x32x16_bf16 v[34:49], v[212:215], v[74:77], v[34:49]
	v_exp_f32_e32 v102, v102
	v_exp_f32_e32 v103, v103
	v_add_f32_e32 v178, v178, v102
	v_add_f32_e32 v218, v218, v103
	v_cvt_pk_bf16_f32 v100, v102, v103
	v_mfma_f32_32x32x16_bf16 v[18:33], v[208:211], v[90:93], v[18:33]
	v_exp_f32_e32 v104, v104
	v_exp_f32_e32 v105, v105
	v_add_f32_e32 v219, v219, v104
	v_add_f32_e32 v220, v220, v105
	v_cvt_pk_bf16_f32 v101, v104, v105
	v_mfma_f32_32x32x16_bf16 v[2:17], v[212:215], v[90:93], v[2:17]
	v_exp_f32_e32 v114, v114
	v_exp_f32_e32 v115, v115
	v_add_f32_e32 v179, v179, v114
	v_add_f32_e32 v221, v221, v115
	v_cvt_pk_bf16_f32 v114, v114, v115
	s_waitcnt lgkmcnt(7)
	v_mfma_f32_32x32x16_bf16 v[66:81], v[184:187], v[130:133], 0
	ds_read_b64_tr_b16 v[208:209], v216 offset:16128
	ds_read_b64_tr_b16 v[210:211], v216 offset:16704
	ds_read_b64_tr_b16 v[212:213], v216 offset:16192
	ds_read_b64_tr_b16 v[214:215], v216 offset:16768
	v_exp_f32_e32 v116, v116
	v_exp_f32_e32 v117, v117
	v_add_f32_e32 v222, v222, v116
	v_add_f32_e32 v223, v223, v117
	v_cvt_pk_bf16_f32 v115, v116, v117
	s_waitcnt lgkmcnt(10)
	v_mfma_f32_32x32x16_bf16 v[66:81], v[188:191], v[134:137], v[66:81]
	v_exp_f32_e32 v118, v118
	v_exp_f32_e32 v119, v119
	v_add_f32_e32 v179, v179, v118
	v_add_f32_e32 v221, v221, v119
	v_cvt_pk_bf16_f32 v116, v118, v119
	s_waitcnt lgkmcnt(9)
	v_mfma_f32_32x32x16_bf16 v[66:81], v[192:195], v[146:149], v[66:81]
	v_exp_f32_e32 v120, v120
	v_exp_f32_e32 v121, v121
	v_add_f32_e32 v222, v222, v120
	v_add_f32_e32 v223, v223, v121
	v_cvt_pk_bf16_f32 v117, v120, v121
	s_waitcnt lgkmcnt(8)
	v_mfma_f32_32x32x16_bf16 v[66:81], v[196:199], v[150:153], v[66:81]
	v_exp_f32_e32 v106, v106
	v_exp_f32_e32 v107, v107
	v_add_f32_e32 v178, v178, v106
	v_add_f32_e32 v218, v218, v107
	v_cvt_pk_bf16_f32 v106, v106, v107
	s_waitcnt lgkmcnt(6)
	v_mfma_f32_32x32x16_bf16 v[50:65], v[200:203], v[98:101], v[50:65]
	v_exp_f32_e32 v108, v108
	v_exp_f32_e32 v109, v109
	v_add_f32_e32 v219, v219, v108
	v_add_f32_e32 v220, v220, v109
	v_cvt_pk_bf16_f32 v107, v108, v109
	s_waitcnt lgkmcnt(4)
	v_mfma_f32_32x32x16_bf16 v[34:49], v[204:207], v[98:101], v[34:49]
	v_exp_f32_e32 v110, v110
	v_exp_f32_e32 v111, v111
	v_add_f32_e32 v178, v178, v110
	v_add_f32_e32 v218, v218, v111
	v_cvt_pk_bf16_f32 v108, v110, v111
	v_mfma_f32_32x32x16_bf16 v[18:33], v[200:203], v[114:117], v[18:33]
	s_waitcnt vmcnt(0)
	v_add_u32_e32 v217, s12, v180
	ds_write_b128 v217, v[162:165]
	ds_write_b128 v217, v[166:169] offset:9216
	v_exp_f32_e32 v112, v112
	v_exp_f32_e32 v113, v113
	v_add_f32_e32 v219, v219, v112
	v_add_f32_e32 v220, v220, v113
	v_cvt_pk_bf16_f32 v109, v112, v113
	v_mfma_f32_32x32x16_bf16 v[2:17], v[204:207], v[114:117], v[2:17]
	v_exp_f32_e32 v122, v122
	v_exp_f32_e32 v123, v123
	v_add_f32_e32 v179, v179, v122
	v_add_f32_e32 v221, v221, v123
	v_cvt_pk_bf16_f32 v122, v122, v123
	v_mfma_f32_32x32x16_bf16 v[82:97], v[184:187], v[154:157], 0
	v_exp_f32_e32 v124, v124
	v_exp_f32_e32 v125, v125
	v_add_f32_e32 v222, v222, v124
	v_add_f32_e32 v223, v223, v125
	v_cvt_pk_bf16_f32 v123, v124, v125
	v_mfma_f32_32x32x16_bf16 v[82:97], v[188:191], v[138:141], v[82:97]
	v_exp_f32_e32 v126, v126
	v_exp_f32_e32 v127, v127
	v_add_f32_e32 v179, v179, v126
	v_add_f32_e32 v221, v221, v127
	v_cvt_pk_bf16_f32 v124, v126, v127
	v_mfma_f32_32x32x16_bf16 v[82:97], v[192:195], v[142:145], v[82:97]
	v_exp_f32_e32 v128, v128
	v_exp_f32_e32 v129, v129
	v_add_f32_e32 v222, v222, v128
	v_add_f32_e32 v223, v223, v129
	v_cvt_pk_bf16_f32 v125, v128, v129
	v_mfma_f32_32x32x16_bf16 v[82:97], v[196:199], v[158:161], v[82:97]
	s_mov_b32 s33, s31
	s_add_i32 s30, s30, 1
	s_cmpk_lt_u32 s30, 0xfe
	s_cbranch_scc1 .Lat_loop
	s_waitcnt lgkmcnt(0)
	s_barrier
	ds_read_b128 v[184:187], v225 offset:4608
	ds_read_b128 v[188:191], v225 offset:4640
	ds_read_b128 v[192:195], v225 offset:4672
	ds_read_b128 v[196:199], v225 offset:4704
	s_add_i32 s31, s33, 0x4800
	s_cmp_eq_u32 s31, 0xd800
	s_cselect_b32 s31, 0, s31
	s_add_i32 s12, s31, 0x4800
	s_cmp_eq_u32 s12, 0xd800
	s_cselect_b32 s12, 0, s12
	v_add_u32_e32 v224, s33, v182
	v_add3_u32 v216, v224, v173, v175
	v_add3_u32 v225, s31, v181, v170
	v_exp_f32_e32 v66, v66
	v_exp_f32_e32 v67, v67
	v_add_f32_e32 v178, v178, v66
	v_add_f32_e32 v218, v218, v67
	v_cvt_pk_bf16_f32 v66, v66, v67
	v_mfma_f32_32x32x16_bf16 v[50:65], v[208:211], v[106:109], v[50:65]
	v_exp_f32_e32 v68, v68
	v_exp_f32_e32 v69, v69
	v_add_f32_e32 v219, v219, v68
	v_add_f32_e32 v220, v220, v69
	v_cvt_pk_bf16_f32 v67, v68, v69
	v_mfma_f32_32x32x16_bf16 v[34:49], v[212:215], v[106:109], v[34:49]
	v_exp_f32_e32 v70, v70
	v_exp_f32_e32 v71, v71
	v_add_f32_e32 v178, v178, v70
	v_add_f32_e32 v218, v218, v71
	v_cvt_pk_bf16_f32 v68, v70, v71
	v_mfma_f32_32x32x16_bf16 v[18:33], v[208:211], v[122:125], v[18:33]
	v_exp_f32_e32 v72, v72
	v_exp_f32_e32 v73, v73
	v_add_f32_e32 v219, v219, v72
	v_add_f32_e32 v220, v220, v73
	v_cvt_pk_bf16_f32 v69, v72, v73
	v_mfma_f32_32x32x16_bf16 v[2:17], v[212:215], v[122:125], v[2:17]
	v_exp_f32_e32 v82, v82
	v_exp_f32_e32 v83, v83
	v_add_f32_e32 v179, v179, v82
	v_add_f32_e32 v221, v221, v83
	v_cvt_pk_bf16_f32 v82, v82, v83
	s_waitcnt lgkmcnt(3)
	v_mfma_f32_32x32x16_bf16 v[98:113], v[184:187], v[130:133], 0
	ds_read_b64_tr_b16 v[200:201], v216 offset:9216
	ds_read_b64_tr_b16 v[202:203], v216 offset:9792
	ds_read_b64_tr_b16 v[204:205], v216 offset:9280
	ds_read_b64_tr_b16 v[206:207], v216 offset:9856
	v_exp_f32_e32 v84, v84
	v_exp_f32_e32 v85, v85
	v_add_f32_e32 v222, v222, v84
	v_add_f32_e32 v223, v223, v85
	v_cvt_pk_bf16_f32 v83, v84, v85
	s_waitcnt lgkmcnt(6)
	v_mfma_f32_32x32x16_bf16 v[98:113], v[188:191], v[134:137], v[98:113]
	ds_read_b64_tr_b16 v[208:209], v216 offset:11520
	ds_read_b64_tr_b16 v[210:211], v216 offset:12096
	ds_read_b64_tr_b16 v[212:213], v216 offset:11584
	ds_read_b64_tr_b16 v[214:215], v216 offset:12160
	v_exp_f32_e32 v86, v86
	v_exp_f32_e32 v87, v87
	v_add_f32_e32 v179, v179, v86
	v_add_f32_e32 v221, v221, v87
	v_cvt_pk_bf16_f32 v84, v86, v87
	s_waitcnt lgkmcnt(9)
	v_mfma_f32_32x32x16_bf16 v[98:113], v[192:195], v[146:149], v[98:113]
	v_exp_f32_e32 v88, v88
	v_exp_f32_e32 v89, v89
	v_add_f32_e32 v222, v222, v88
	v_add_f32_e32 v223, v223, v89
	v_cvt_pk_bf16_f32 v85, v88, v89
	s_waitcnt lgkmcnt(8)
	v_mfma_f32_32x32x16_bf16 v[98:113], v[196:199], v[150:153], v[98:113]
	v_exp_f32_e32 v74, v74
	v_exp_f32_e32 v75, v75
	v_add_f32_e32 v178, v178, v74
	v_add_f32_e32 v218, v218, v75
	v_cvt_pk_bf16_f32 v74, v74, v75
	v_mfma_f32_32x32x16_bf16 v[114:129], v[184:187], v[154:157], 0
	v_exp_f32_e32 v76, v76
	v_exp_f32_e32 v77, v77
	v_add_f32_e32 v219, v219, v76
	v_add_f32_e32 v220, v220, v77
	v_cvt_pk_bf16_f32 v75, v76, v77
	v_mfma_f32_32x32x16_bf16 v[114:129], v[188:191], v[138:141], v[114:129]
	v_exp_f32_e32 v78, v78
	v_exp_f32_e32 v79, v79
	v_add_f32_e32 v178, v178, v78
	v_add_f32_e32 v218, v218, v79
	v_cvt_pk_bf16_f32 v76, v78, v79
	v_mfma_f32_32x32x16_bf16 v[114:129], v[192:195], v[142:145], v[114:129]
	v_exp_f32_e32 v80, v80
	v_exp_f32_e32 v81, v81
	v_add_f32_e32 v219, v219, v80
	v_add_f32_e32 v220, v220, v81
	v_cvt_pk_bf16_f32 v77, v80, v81
	v_mfma_f32_32x32x16_bf16 v[114:129], v[196:199], v[158:161], v[114:129]
	v_exp_f32_e32 v90, v90
	v_exp_f32_e32 v91, v91
	v_add_f32_e32 v179, v179, v90
	v_add_f32_e32 v221, v221, v91
	v_cvt_pk_bf16_f32 v90, v90, v91
	s_waitcnt lgkmcnt(6)
	v_mfma_f32_32x32x16_bf16 v[50:65], v[200:203], v[66:69], v[50:65]
	ds_read_b128 v[184:187], v225
	ds_read_b128 v[188:191], v225 offset:32
	ds_read_b128 v[192:195], v225 offset:64
	ds_read_b128 v[196:199], v225 offset:96
	v_exp_f32_e32 v92, v92
	v_exp_f32_e32 v93, v93
	v_add_f32_e32 v222, v222, v92
	v_add_f32_e32 v223, v223, v93
	v_cvt_pk_bf16_f32 v91, v92, v93
	s_waitcnt lgkmcnt(8)
	v_mfma_f32_32x32x16_bf16 v[34:49], v[204:207], v[66:69], v[34:49]
	v_exp_f32_e32 v94, v94
	v_exp_f32_e32 v95, v95
	v_add_f32_e32 v179, v179, v94
	v_add_f32_e32 v221, v221, v95
	v_cvt_pk_bf16_f32 v92, v94, v95
	v_mfma_f32_32x32x16_bf16 v[18:33], v[200:203], v[82:85], v[18:33]
	v_exp_f32_e32 v96, v96
	v_exp_f32_e32 v97, v97
	v_add_f32_e32 v222, v222, v96
	v_add_f32_e32 v223, v223, v97
	v_cvt_pk_bf16_f32 v93, v96, v97
	v_mfma_f32_32x32x16_bf16 v[2:17], v[204:207], v[82:85], v[2:17]
	v_exp_f32_e32 v98, v98
	v_exp_f32_e32 v99, v99
	v_add_f32_e32 v178, v178, v98
	v_add_f32_e32 v218, v218, v99
	v_cvt_pk_bf16_f32 v98, v98, v99
	s_waitcnt lgkmcnt(6)
	v_mfma_f32_32x32x16_bf16 v[50:65], v[208:211], v[74:77], v[50:65]
	ds_read_b64_tr_b16 v[200:201], v216 offset:13824
	ds_read_b64_tr_b16 v[202:203], v216 offset:14400
	ds_read_b64_tr_b16 v[204:205], v216 offset:13888
	ds_read_b64_tr_b16 v[206:207], v216 offset:14464
	v_exp_f32_e32 v100, v100
	v_exp_f32_e32 v101, v101
	v_add_f32_e32 v219, v219, v100
	v_add_f32_e32 v220, v220, v101
	v_cvt_pk_bf16_f32 v99, v100, v101
	s_waitcnt lgkmcnt(8)
	v_mfma_f32_32x32x16_bf16 v[34:49], v[212:215], v[74:77], v[34:49]
	v_exp_f32_e32 v102, v102
	v_exp_f32_e32 v103, v103
	v_add_f32_e32 v178, v178, v102
	v_add_f32_e32 v218, v218, v103
	v_cvt_pk_bf16_f32 v100, v102, v103
	v_mfma_f32_32x32x16_bf16 v[18:33], v[208:211], v[90:93], v[18:33]
	v_exp_f32_e32 v104, v104
	v_exp_f32_e32 v105, v105
	v_add_f32_e32 v219, v219, v104
	v_add_f32_e32 v220, v220, v105
	v_cvt_pk_bf16_f32 v101, v104, v105
	v_mfma_f32_32x32x16_bf16 v[2:17], v[212:215], v[90:93], v[2:17]
	v_exp_f32_e32 v114, v114
	v_exp_f32_e32 v115, v115
	v_add_f32_e32 v179, v179, v114
	v_add_f32_e32 v221, v221, v115
	v_cvt_pk_bf16_f32 v114, v114, v115
	s_waitcnt lgkmcnt(7)
	v_mfma_f32_32x32x16_bf16 v[66:81], v[184:187], v[130:133], 0
	ds_read_b64_tr_b16 v[208:209], v216 offset:16128
	ds_read_b64_tr_b16 v[210:211], v216 offset:16704
	ds_read_b64_tr_b16 v[212:213], v216 offset:16192
	ds_read_b64_tr_b16 v[214:215], v216 offset:16768
	v_exp_f32_e32 v116, v116
	v_exp_f32_e32 v117, v117
	v_add_f32_e32 v222, v222, v116
	v_add_f32_e32 v223, v223, v117
	v_cvt_pk_bf16_f32 v115, v116, v117
	s_waitcnt lgkmcnt(10)
	v_mfma_f32_32x32x16_bf16 v[66:81], v[188:191], v[134:137], v[66:81]
	v_exp_f32_e32 v118, v118
	v_exp_f32_e32 v119, v119
	v_add_f32_e32 v179, v179, v118
	v_add_f32_e32 v221, v221, v119
	v_cvt_pk_bf16_f32 v116, v118, v119
	s_waitcnt lgkmcnt(9)
	v_mfma_f32_32x32x16_bf16 v[66:81], v[192:195], v[146:149], v[66:81]
	v_exp_f32_e32 v120, v120
	v_exp_f32_e32 v121, v121
	v_add_f32_e32 v222, v222, v120
	v_add_f32_e32 v223, v223, v121
	v_cvt_pk_bf16_f32 v117, v120, v121
	s_waitcnt lgkmcnt(8)
	v_mfma_f32_32x32x16_bf16 v[66:81], v[196:199], v[150:153], v[66:81]
	v_exp_f32_e32 v106, v106
	v_exp_f32_e32 v107, v107
	v_add_f32_e32 v178, v178, v106
	v_add_f32_e32 v218, v218, v107
	v_cvt_pk_bf16_f32 v106, v106, v107
	s_waitcnt lgkmcnt(6)
	v_mfma_f32_32x32x16_bf16 v[50:65], v[200:203], v[98:101], v[50:65]
	v_exp_f32_e32 v108, v108
	v_exp_f32_e32 v109, v109
	v_add_f32_e32 v219, v219, v108
	v_add_f32_e32 v220, v220, v109
	v_cvt_pk_bf16_f32 v107, v108, v109
	s_waitcnt lgkmcnt(4)
	v_mfma_f32_32x32x16_bf16 v[34:49], v[204:207], v[98:101], v[34:49]
	v_exp_f32_e32 v110, v110
	v_exp_f32_e32 v111, v111
	v_add_f32_e32 v178, v178, v110
	v_add_f32_e32 v218, v218, v111
	v_cvt_pk_bf16_f32 v108, v110, v111
	v_mfma_f32_32x32x16_bf16 v[18:33], v[200:203], v[114:117], v[18:33]
	v_exp_f32_e32 v112, v112
	v_exp_f32_e32 v113, v113
	v_add_f32_e32 v219, v219, v112
	v_add_f32_e32 v220, v220, v113
	v_cvt_pk_bf16_f32 v109, v112, v113
	v_mfma_f32_32x32x16_bf16 v[2:17], v[204:207], v[114:117], v[2:17]
	v_exp_f32_e32 v122, v122
	v_exp_f32_e32 v123, v123
	v_add_f32_e32 v179, v179, v122
	v_add_f32_e32 v221, v221, v123
	v_cvt_pk_bf16_f32 v122, v122, v123
	v_mfma_f32_32x32x16_bf16 v[82:97], v[184:187], v[154:157], 0
	v_exp_f32_e32 v124, v124
	v_exp_f32_e32 v125, v125
	v_add_f32_e32 v222, v222, v124
	v_add_f32_e32 v223, v223, v125
	v_cvt_pk_bf16_f32 v123, v124, v125
	v_mfma_f32_32x32x16_bf16 v[82:97], v[188:191], v[138:141], v[82:97]
	v_exp_f32_e32 v126, v126
	v_exp_f32_e32 v127, v127
	v_add_f32_e32 v179, v179, v126
	v_add_f32_e32 v221, v221, v127
	v_cvt_pk_bf16_f32 v124, v126, v127
	v_mfma_f32_32x32x16_bf16 v[82:97], v[192:195], v[142:145], v[82:97]
	v_exp_f32_e32 v128, v128
	v_exp_f32_e32 v129, v129
	v_add_f32_e32 v222, v222, v128
	v_add_f32_e32 v223, v223, v129
	v_cvt_pk_bf16_f32 v125, v128, v129
	v_mfma_f32_32x32x16_bf16 v[82:97], v[196:199], v[158:161], v[82:97]
	s_mov_b32 s33, s31
	s_waitcnt lgkmcnt(0)
	s_barrier
	ds_read_b128 v[184:187], v225 offset:4608
	ds_read_b128 v[188:191], v225 offset:4640
	ds_read_b128 v[192:195], v225 offset:4672
	ds_read_b128 v[196:199], v225 offset:4704
	s_add_i32 s31, s33, 0x4800
	s_cmp_eq_u32 s31, 0xd800
	s_cselect_b32 s31, 0, s31
	s_add_i32 s12, s31, 0x4800
	s_cmp_eq_u32 s12, 0xd800
	s_cselect_b32 s12, 0, s12
	v_add_u32_e32 v224, s33, v182
	v_add3_u32 v216, v224, v173, v175
	v_add3_u32 v225, s31, v181, v170
	v_exp_f32_e32 v66, v66
	v_exp_f32_e32 v67, v67
	v_add_f32_e32 v178, v178, v66
	v_add_f32_e32 v218, v218, v67
	v_cvt_pk_bf16_f32 v66, v66, v67
	v_mfma_f32_32x32x16_bf16 v[50:65], v[208:211], v[106:109], v[50:65]
	v_exp_f32_e32 v68, v68
	v_exp_f32_e32 v69, v69
	v_add_f32_e32 v219, v219, v68
	v_add_f32_e32 v220, v220, v69
	v_cvt_pk_bf16_f32 v67, v68, v69
	v_mfma_f32_32x32x16_bf16 v[34:49], v[212:215], v[106:109], v[34:49]
	v_exp_f32_e32 v70, v70
	v_exp_f32_e32 v71, v71
	v_add_f32_e32 v178, v178, v70
	v_add_f32_e32 v218, v218, v71
	v_cvt_pk_bf16_f32 v68, v70, v71
	v_mfma_f32_32x32x16_bf16 v[18:33], v[208:211], v[122:125], v[18:33]
	v_exp_f32_e32 v72, v72
	v_exp_f32_e32 v73, v73
	v_add_f32_e32 v219, v219, v72
	v_add_f32_e32 v220, v220, v73
	v_cvt_pk_bf16_f32 v69, v72, v73
	v_mfma_f32_32x32x16_bf16 v[2:17], v[212:215], v[122:125], v[2:17]
	v_exp_f32_e32 v82, v82
	v_exp_f32_e32 v83, v83
	v_add_f32_e32 v179, v179, v82
	v_add_f32_e32 v221, v221, v83
	v_cvt_pk_bf16_f32 v82, v82, v83
	s_waitcnt lgkmcnt(3)
	v_mfma_f32_32x32x16_bf16 v[98:113], v[184:187], v[130:133], 0
	ds_read_b64_tr_b16 v[200:201], v216 offset:9216
	ds_read_b64_tr_b16 v[202:203], v216 offset:9792
	ds_read_b64_tr_b16 v[204:205], v216 offset:9280
	ds_read_b64_tr_b16 v[206:207], v216 offset:9856
	v_exp_f32_e32 v84, v84
	v_exp_f32_e32 v85, v85
	v_add_f32_e32 v222, v222, v84
	v_add_f32_e32 v223, v223, v85
	v_cvt_pk_bf16_f32 v83, v84, v85
	s_waitcnt lgkmcnt(6)
	v_mfma_f32_32x32x16_bf16 v[98:113], v[188:191], v[134:137], v[98:113]
	ds_read_b64_tr_b16 v[208:209], v216 offset:11520
	ds_read_b64_tr_b16 v[210:211], v216 offset:12096
	ds_read_b64_tr_b16 v[212:213], v216 offset:11584
	ds_read_b64_tr_b16 v[214:215], v216 offset:12160
	v_exp_f32_e32 v86, v86
	v_exp_f32_e32 v87, v87
	v_add_f32_e32 v179, v179, v86
	v_add_f32_e32 v221, v221, v87
	v_cvt_pk_bf16_f32 v84, v86, v87
	s_waitcnt lgkmcnt(9)
	v_mfma_f32_32x32x16_bf16 v[98:113], v[192:195], v[146:149], v[98:113]
	v_exp_f32_e32 v88, v88
	v_exp_f32_e32 v89, v89
	v_add_f32_e32 v222, v222, v88
	v_add_f32_e32 v223, v223, v89
	v_cvt_pk_bf16_f32 v85, v88, v89
	s_waitcnt lgkmcnt(8)
	v_mfma_f32_32x32x16_bf16 v[98:113], v[196:199], v[150:153], v[98:113]
	v_exp_f32_e32 v74, v74
	v_exp_f32_e32 v75, v75
	v_add_f32_e32 v178, v178, v74
	v_add_f32_e32 v218, v218, v75
	v_cvt_pk_bf16_f32 v74, v74, v75
	v_mfma_f32_32x32x16_bf16 v[114:129], v[184:187], v[154:157], 0
	v_exp_f32_e32 v76, v76
	v_exp_f32_e32 v77, v77
	v_add_f32_e32 v219, v219, v76
	v_add_f32_e32 v220, v220, v77
	v_cvt_pk_bf16_f32 v75, v76, v77
	v_mfma_f32_32x32x16_bf16 v[114:129], v[188:191], v[138:141], v[114:129]
	v_exp_f32_e32 v78, v78
	v_exp_f32_e32 v79, v79
	v_add_f32_e32 v178, v178, v78
	v_add_f32_e32 v218, v218, v79
	v_cvt_pk_bf16_f32 v76, v78, v79
	v_mfma_f32_32x32x16_bf16 v[114:129], v[192:195], v[142:145], v[114:129]
	v_exp_f32_e32 v80, v80
	v_exp_f32_e32 v81, v81
	v_add_f32_e32 v219, v219, v80
	v_add_f32_e32 v220, v220, v81
	v_cvt_pk_bf16_f32 v77, v80, v81
	v_mfma_f32_32x32x16_bf16 v[114:129], v[196:199], v[158:161], v[114:129]
	v_exp_f32_e32 v90, v90
	v_exp_f32_e32 v91, v91
	v_add_f32_e32 v179, v179, v90
	v_add_f32_e32 v221, v221, v91
	v_cvt_pk_bf16_f32 v90, v90, v91
	s_waitcnt lgkmcnt(6)
	v_mfma_f32_32x32x16_bf16 v[50:65], v[200:203], v[66:69], v[50:65]
	ds_read_b128 v[184:187], v225
	ds_read_b128 v[188:191], v225 offset:32
	ds_read_b128 v[192:195], v225 offset:64
	ds_read_b128 v[196:199], v225 offset:96
	v_exp_f32_e32 v92, v92
	v_exp_f32_e32 v93, v93
	v_add_f32_e32 v222, v222, v92
	v_add_f32_e32 v223, v223, v93
	v_cvt_pk_bf16_f32 v91, v92, v93
	s_waitcnt lgkmcnt(8)
	v_mfma_f32_32x32x16_bf16 v[34:49], v[204:207], v[66:69], v[34:49]
	v_exp_f32_e32 v94, v94
	v_exp_f32_e32 v95, v95
	v_add_f32_e32 v179, v179, v94
	v_add_f32_e32 v221, v221, v95
	v_cvt_pk_bf16_f32 v92, v94, v95
	v_mfma_f32_32x32x16_bf16 v[18:33], v[200:203], v[82:85], v[18:33]
	v_exp_f32_e32 v96, v96
	v_exp_f32_e32 v97, v97
	v_add_f32_e32 v222, v222, v96
	v_add_f32_e32 v223, v223, v97
	v_cvt_pk_bf16_f32 v93, v96, v97
	v_mfma_f32_32x32x16_bf16 v[2:17], v[204:207], v[82:85], v[2:17]
	v_exp_f32_e32 v98, v98
	v_exp_f32_e32 v99, v99
	v_add_f32_e32 v178, v178, v98
	v_add_f32_e32 v218, v218, v99
	v_cvt_pk_bf16_f32 v98, v98, v99
	s_waitcnt lgkmcnt(6)
	v_mfma_f32_32x32x16_bf16 v[50:65], v[208:211], v[74:77], v[50:65]
	ds_read_b64_tr_b16 v[200:201], v216 offset:13824
	ds_read_b64_tr_b16 v[202:203], v216 offset:14400
	ds_read_b64_tr_b16 v[204:205], v216 offset:13888
	ds_read_b64_tr_b16 v[206:207], v216 offset:14464
	v_exp_f32_e32 v100, v100
	v_exp_f32_e32 v101, v101
	v_add_f32_e32 v219, v219, v100
	v_add_f32_e32 v220, v220, v101
	v_cvt_pk_bf16_f32 v99, v100, v101
	s_waitcnt lgkmcnt(8)
	v_mfma_f32_32x32x16_bf16 v[34:49], v[212:215], v[74:77], v[34:49]
	v_exp_f32_e32 v102, v102
	v_exp_f32_e32 v103, v103
	v_add_f32_e32 v178, v178, v102
	v_add_f32_e32 v218, v218, v103
	v_cvt_pk_bf16_f32 v100, v102, v103
	v_mfma_f32_32x32x16_bf16 v[18:33], v[208:211], v[90:93], v[18:33]
	v_exp_f32_e32 v104, v104
	v_exp_f32_e32 v105, v105
	v_add_f32_e32 v219, v219, v104
	v_add_f32_e32 v220, v220, v105
	v_cvt_pk_bf16_f32 v101, v104, v105
	v_mfma_f32_32x32x16_bf16 v[2:17], v[212:215], v[90:93], v[2:17]
	v_exp_f32_e32 v114, v114
	v_exp_f32_e32 v115, v115
	v_add_f32_e32 v179, v179, v114
	v_add_f32_e32 v221, v221, v115
	v_cvt_pk_bf16_f32 v114, v114, v115
	s_waitcnt lgkmcnt(7)
	v_mfma_f32_32x32x16_bf16 v[66:81], v[184:187], v[130:133], 0
	ds_read_b64_tr_b16 v[208:209], v216 offset:16128
	ds_read_b64_tr_b16 v[210:211], v216 offset:16704
	ds_read_b64_tr_b16 v[212:213], v216 offset:16192
	ds_read_b64_tr_b16 v[214:215], v216 offset:16768
	v_exp_f32_e32 v116, v116
	v_exp_f32_e32 v117, v117
	v_add_f32_e32 v222, v222, v116
	v_add_f32_e32 v223, v223, v117
	v_cvt_pk_bf16_f32 v115, v116, v117
	s_waitcnt lgkmcnt(10)
	v_mfma_f32_32x32x16_bf16 v[66:81], v[188:191], v[134:137], v[66:81]
	v_exp_f32_e32 v118, v118
	v_exp_f32_e32 v119, v119
	v_add_f32_e32 v179, v179, v118
	v_add_f32_e32 v221, v221, v119
	v_cvt_pk_bf16_f32 v116, v118, v119
	s_waitcnt lgkmcnt(9)
	v_mfma_f32_32x32x16_bf16 v[66:81], v[192:195], v[146:149], v[66:81]
	v_exp_f32_e32 v120, v120
	v_exp_f32_e32 v121, v121
	v_add_f32_e32 v222, v222, v120
	v_add_f32_e32 v223, v223, v121
	v_cvt_pk_bf16_f32 v117, v120, v121
	s_waitcnt lgkmcnt(8)
	v_mfma_f32_32x32x16_bf16 v[66:81], v[196:199], v[150:153], v[66:81]
	v_exp_f32_e32 v106, v106
	v_exp_f32_e32 v107, v107
	v_add_f32_e32 v178, v178, v106
	v_add_f32_e32 v218, v218, v107
	v_cvt_pk_bf16_f32 v106, v106, v107
	s_waitcnt lgkmcnt(6)
	v_mfma_f32_32x32x16_bf16 v[50:65], v[200:203], v[98:101], v[50:65]
	v_exp_f32_e32 v108, v108
	v_exp_f32_e32 v109, v109
	v_add_f32_e32 v219, v219, v108
	v_add_f32_e32 v220, v220, v109
	v_cvt_pk_bf16_f32 v107, v108, v109
	s_waitcnt lgkmcnt(4)
	v_mfma_f32_32x32x16_bf16 v[34:49], v[204:207], v[98:101], v[34:49]
	v_exp_f32_e32 v110, v110
	v_exp_f32_e32 v111, v111
	v_add_f32_e32 v178, v178, v110
	v_add_f32_e32 v218, v218, v111
	v_cvt_pk_bf16_f32 v108, v110, v111
	v_mfma_f32_32x32x16_bf16 v[18:33], v[200:203], v[114:117], v[18:33]
	v_exp_f32_e32 v112, v112
	v_exp_f32_e32 v113, v113
	v_add_f32_e32 v219, v219, v112
	v_add_f32_e32 v220, v220, v113
	v_cvt_pk_bf16_f32 v109, v112, v113
	v_mfma_f32_32x32x16_bf16 v[2:17], v[204:207], v[114:117], v[2:17]
	v_exp_f32_e32 v122, v122
	v_exp_f32_e32 v123, v123
	v_add_f32_e32 v179, v179, v122
	v_add_f32_e32 v221, v221, v123
	v_cvt_pk_bf16_f32 v122, v122, v123
	v_mfma_f32_32x32x16_bf16 v[82:97], v[184:187], v[154:157], 0
	v_exp_f32_e32 v124, v124
	v_exp_f32_e32 v125, v125
	v_add_f32_e32 v222, v222, v124
	v_add_f32_e32 v223, v223, v125
	v_cvt_pk_bf16_f32 v123, v124, v125
	v_mfma_f32_32x32x16_bf16 v[82:97], v[188:191], v[138:141], v[82:97]
	v_exp_f32_e32 v126, v126
	v_exp_f32_e32 v127, v127
	v_add_f32_e32 v179, v179, v126
	v_add_f32_e32 v221, v221, v127
	v_cvt_pk_bf16_f32 v124, v126, v127
	v_mfma_f32_32x32x16_bf16 v[82:97], v[192:195], v[142:145], v[82:97]
	v_exp_f32_e32 v128, v128
	v_exp_f32_e32 v129, v129
	v_add_f32_e32 v222, v222, v128
	v_add_f32_e32 v223, v223, v129
	v_cvt_pk_bf16_f32 v125, v128, v129
	v_mfma_f32_32x32x16_bf16 v[82:97], v[196:199], v[158:161], v[82:97]
	s_mov_b32 s33, s31
	s_waitcnt lgkmcnt(2)
	v_mfma_f32_32x32x16_bf16 v[50:65], v[208:211], v[106:109], v[50:65]
	s_waitcnt lgkmcnt(0)
	v_mfma_f32_32x32x16_bf16 v[34:49], v[212:215], v[106:109], v[34:49]
	v_mfma_f32_32x32x16_bf16 v[18:33], v[208:211], v[122:125], v[18:33]
	v_mfma_f32_32x32x16_bf16 v[2:17], v[212:215], v[122:125], v[2:17]
	v_add_f32_e32 v178, v178, v218
	v_add_f32_e32 v219, v219, v220
	v_add_f32_e32 v179, v179, v221
	v_add_f32_e32 v222, v222, v223
	v_add_f32_e32 v178, v178, v219
	v_add_f32_e32 v179, v179, v222
	s_branch .LBB0_299
